# in-proj V-transpose tiles: 2-lane DPP exchange + v_perm, 64 dword stores instead of 128 short stores per wave; on top of v6
# baseline (speedup 1.0000x reference)
; __device__ __forceinline__ unsigned cvt_pk_bf16(float lo, float hi) { unsigned r; asm volatile("v_cvt_pk_bf16_f32 %0, %1, %2" : "=v"(r) : "v"(lo), "v"(hi)); return r; }
;     __device__ __forceinline__ void operator()(const f32x4 (&acc)[2][2][4][2], const Unit& u, int wr, int wc, int fr_, int fq_) const {
;     ...
;         } else if (pn == 7 || pn == 8) {
; #pragma unroll
;             for (int ai = 0; ai < 2; ++ai)
; #pragma unroll
;                 for (int m = 0; m < 4; ++m) {
;                     const int row = u.pm * 256 + ai * 128 + wr * 64 + m * 16 + fr;
;                     const float rs = rs8[ai][m];
;                     bf16_t* dst = VB + (size_t)(256 * (pn - 7) + 64 * wc + 16 * fq) * Mg + row;
; #pragma unroll
;                     for (int bj = 0; bj < 2; ++bj)
; #pragma unroll
;                         for (int n = 0; n < 2; ++n) { const f32x4 a = acc[ai][bj][m][n] * rs; const unsigned w0 = cvt_pk_bf16(a[0], a[1]), w1 = cvt_pk_bf16(a[2], a[3]);
;                             bf16_t* d = dst + (size_t)(8 * bj + 4 * n) * Mg;
;                             d[0] = (bf16_t)w0; d[(size_t)Mg] = (bf16_t)(w0 >> 16); d[2 * (size_t)Mg] = (bf16_t)w1; d[3 * (size_t)Mg] = (bf16_t)(w1 >> 16); }
;                 }
.LBB0_419:
	s_andn2_b64 vcc, exec, s[0:1]
	s_cbranch_vccnz .LBB0_421
	s_lshl_b32 s0, s40, 8
	v_readlane_b32 s1, v255, 40
	s_add_i32 s0, s1, s0
	v_lshl_add_u32 v226, v188, 4, s0
	v_readlane_b32 s0, v255, 48
	v_and_b32_e32 v232, 1, v203
	v_sub_u32_e32 v232, 0, v232
	v_mov_b32_e32 v227, 2
	v_lshlrev_b32_e32 v226, s0, v226
	v_lshlrev_b32_e32 v227, s0, v227
	v_add_u32_e32 v226, v226, v186
	v_lshlrev_b32_e32 v226, 1, v226
	v_add_u32_e32 v229, -2, v227
	v_and_b32_e32 v228, v229, v232
	v_add_u32_e32 v242, v226, v228
	v_and_b32_e32 v230, 0xfdfe0606, v232
	v_add_u32_e32 v230, 0x5040100, v230
	v_lshlrev_b32_e32 v240, 1, v227
	v_lshlrev_b32_e32 v241, 2, v227
	v_readlane_b32 s0, v253, 19
	v_readlane_b32 s1, v253, 20
	v_add_u32_e32 v246, v242, v240
	v_add_u32_e32 v243, v242, v241
	v_add_u32_e32 v247, v243, v240
	v_add_u32_e32 v244, v243, v241
	v_add_u32_e32 v248, v244, v240
	v_add_u32_e32 v245, v244, v241
	v_add_u32_e32 v249, v245, v240
	v_mul_f32_e32 v118, v0, v118
	v_mul_f32_e32 v119, v0, v119
	v_mul_f32_e32 v120, v0, v120
	v_mul_f32_e32 v121, v0, v121
	v_mul_f32_e32 v114, v0, v114
	v_mul_f32_e32 v115, v0, v115
	v_mul_f32_e32 v116, v0, v116
	v_mul_f32_e32 v117, v0, v117
	v_mul_f32_e32 v126, v0, v126
	v_mul_f32_e32 v127, v0, v127
	v_mul_f32_e32 v128, v0, v128
	v_mul_f32_e32 v129, v0, v129
	v_mul_f32_e32 v122, v0, v122
	v_mul_f32_e32 v123, v0, v123
	v_mul_f32_e32 v124, v0, v124
	v_mul_f32_e32 v125, v0, v125
	v_cvt_pk_bf16_f32 v118, v118, v119
	v_cvt_pk_bf16_f32 v119, v120, v121
	v_cvt_pk_bf16_f32 v114, v114, v115
	v_cvt_pk_bf16_f32 v115, v116, v117
	v_cvt_pk_bf16_f32 v126, v126, v127
	v_cvt_pk_bf16_f32 v127, v128, v129
	v_cvt_pk_bf16_f32 v122, v122, v123
	v_cvt_pk_bf16_f32 v123, v124, v125
	v_mov_b32_dpp v120, v118 quad_perm:[1,0,3,2] row_mask:0xf bank_mask:0xf
	v_mov_b32_dpp v121, v119 quad_perm:[1,0,3,2] row_mask:0xf bank_mask:0xf
	v_mov_b32_dpp v116, v114 quad_perm:[1,0,3,2] row_mask:0xf bank_mask:0xf
	v_mov_b32_dpp v117, v115 quad_perm:[1,0,3,2] row_mask:0xf bank_mask:0xf
	v_mov_b32_dpp v128, v126 quad_perm:[1,0,3,2] row_mask:0xf bank_mask:0xf
	v_mov_b32_dpp v129, v127 quad_perm:[1,0,3,2] row_mask:0xf bank_mask:0xf
	v_mov_b32_dpp v124, v122 quad_perm:[1,0,3,2] row_mask:0xf bank_mask:0xf
	v_mov_b32_dpp v125, v123 quad_perm:[1,0,3,2] row_mask:0xf bank_mask:0xf
	v_perm_b32 v118, v120, v118, v230
	v_perm_b32 v119, v121, v119, v230
	v_perm_b32 v114, v116, v114, v230
	v_perm_b32 v115, v117, v115, v230
	v_perm_b32 v126, v128, v126, v230
	v_perm_b32 v127, v129, v127, v230
	v_perm_b32 v122, v124, v122, v230
	v_perm_b32 v123, v125, v123, v230
	global_store_dword v242, v118, s[0:1]
	global_store_dword v246, v119, s[0:1]
	global_store_dword v243, v114, s[0:1]
	global_store_dword v247, v115, s[0:1]
	global_store_dword v244, v126, s[0:1]
	global_store_dword v248, v127, s[0:1]
	global_store_dword v245, v122, s[0:1]
	global_store_dword v249, v123, s[0:1]
	v_mul_f32_e32 v106, v154, v106
	v_mul_f32_e32 v107, v154, v107
	v_mul_f32_e32 v108, v154, v108
	v_mul_f32_e32 v109, v154, v109
	v_mul_f32_e32 v98, v154, v98
	v_mul_f32_e32 v99, v154, v99
	v_mul_f32_e32 v100, v154, v100
	v_mul_f32_e32 v101, v154, v101
	v_mul_f32_e32 v110, v154, v110
	v_mul_f32_e32 v111, v154, v111
	v_mul_f32_e32 v112, v154, v112
	v_mul_f32_e32 v113, v154, v113
	v_mul_f32_e32 v102, v154, v102
	v_mul_f32_e32 v103, v154, v103
	v_mul_f32_e32 v104, v154, v104
	v_mul_f32_e32 v105, v154, v105
	v_cvt_pk_bf16_f32 v106, v106, v107
	v_cvt_pk_bf16_f32 v107, v108, v109
	v_cvt_pk_bf16_f32 v98, v98, v99
	v_cvt_pk_bf16_f32 v99, v100, v101
	v_cvt_pk_bf16_f32 v110, v110, v111
	v_cvt_pk_bf16_f32 v111, v112, v113
	v_cvt_pk_bf16_f32 v102, v102, v103
	v_cvt_pk_bf16_f32 v103, v104, v105
	v_mov_b32_dpp v108, v106 quad_perm:[1,0,3,2] row_mask:0xf bank_mask:0xf
	v_mov_b32_dpp v109, v107 quad_perm:[1,0,3,2] row_mask:0xf bank_mask:0xf
	v_mov_b32_dpp v100, v98 quad_perm:[1,0,3,2] row_mask:0xf bank_mask:0xf
	v_mov_b32_dpp v101, v99 quad_perm:[1,0,3,2] row_mask:0xf bank_mask:0xf
	v_mov_b32_dpp v112, v110 quad_perm:[1,0,3,2] row_mask:0xf bank_mask:0xf
	v_mov_b32_dpp v113, v111 quad_perm:[1,0,3,2] row_mask:0xf bank_mask:0xf
	v_mov_b32_dpp v104, v102 quad_perm:[1,0,3,2] row_mask:0xf bank_mask:0xf
	v_mov_b32_dpp v105, v103 quad_perm:[1,0,3,2] row_mask:0xf bank_mask:0xf
	v_perm_b32 v106, v108, v106, v230
	v_perm_b32 v107, v109, v107, v230
	v_perm_b32 v98, v100, v98, v230
	v_perm_b32 v99, v101, v99, v230
	v_perm_b32 v110, v112, v110, v230
	v_perm_b32 v111, v113, v111, v230
	v_perm_b32 v102, v104, v102, v230
	v_perm_b32 v103, v105, v103, v230
	global_store_dword v242, v106, s[0:1] offset:32
	global_store_dword v246, v107, s[0:1] offset:32
	global_store_dword v243, v98, s[0:1] offset:32
	global_store_dword v247, v99, s[0:1] offset:32
	global_store_dword v244, v110, s[0:1] offset:32
	global_store_dword v248, v111, s[0:1] offset:32
	global_store_dword v245, v102, s[0:1] offset:32
	global_store_dword v249, v103, s[0:1] offset:32
	v_mul_f32_e32 v90, v148, v90
	v_mul_f32_e32 v91, v148, v91
	v_mul_f32_e32 v92, v148, v92
	v_mul_f32_e32 v93, v148, v93
	v_mul_f32_e32 v82, v148, v82
	v_mul_f32_e32 v83, v148, v83
	v_mul_f32_e32 v84, v148, v84
	v_mul_f32_e32 v85, v148, v85
	v_mul_f32_e32 v94, v148, v94
	v_mul_f32_e32 v95, v148, v95
	v_mul_f32_e32 v96, v148, v96
	v_mul_f32_e32 v97, v148, v97
	v_mul_f32_e32 v86, v148, v86
	v_mul_f32_e32 v87, v148, v87
	v_mul_f32_e32 v88, v148, v88
	v_mul_f32_e32 v89, v148, v89
	v_cvt_pk_bf16_f32 v90, v90, v91
	v_cvt_pk_bf16_f32 v91, v92, v93
	v_cvt_pk_bf16_f32 v82, v82, v83
	v_cvt_pk_bf16_f32 v83, v84, v85
	v_cvt_pk_bf16_f32 v94, v94, v95
	v_cvt_pk_bf16_f32 v95, v96, v97
	v_cvt_pk_bf16_f32 v86, v86, v87
; __device__ __forceinline__ unsigned cvt_pk_bf16(float lo, float hi) { unsigned r; asm volatile("v_cvt_pk_bf16_f32 %0, %1, %2" : "=v"(r) : "v"(lo), "v"(hi)); return r; }
;     __device__ __forceinline__ void operator()(const f32x4 (&acc)[2][2][4][2], const Unit& u, int wr, int wc, int fr_, int fq_) const {
;     ...
;         } else if (pn == 7 || pn == 8) {
; #pragma unroll
;             for (int ai = 0; ai < 2; ++ai)
; #pragma unroll
;                 for (int m = 0; m < 4; ++m) {
;                     const int row = u.pm * 256 + ai * 128 + wr * 64 + m * 16 + fr;
;                     const float rs = rs8[ai][m];
;                     bf16_t* dst = VB + (size_t)(256 * (pn - 7) + 64 * wc + 16 * fq) * Mg + row;
; #pragma unroll
;                     for (int bj = 0; bj < 2; ++bj)
; #pragma unroll
;                         for (int n = 0; n < 2; ++n) { const f32x4 a = acc[ai][bj][m][n] * rs; const unsigned w0 = cvt_pk_bf16(a[0], a[1]), w1 = cvt_pk_bf16(a[2], a[3]);
;                             bf16_t* d = dst + (size_t)(8 * bj + 4 * n) * Mg;
;                             d[0] = (bf16_t)w0; d[(size_t)Mg] = (bf16_t)(w0 >> 16); d[2 * (size_t)Mg] = (bf16_t)w1; d[3 * (size_t)Mg] = (bf16_t)(w1 >> 16); }
;                 }
	v_cvt_pk_bf16_f32 v87, v88, v89
	v_mov_b32_dpp v92, v90 quad_perm:[1,0,3,2] row_mask:0xf bank_mask:0xf
	v_mov_b32_dpp v93, v91 quad_perm:[1,0,3,2] row_mask:0xf bank_mask:0xf
	v_mov_b32_dpp v84, v82 quad_perm:[1,0,3,2] row_mask:0xf bank_mask:0xf
	v_mov_b32_dpp v85, v83 quad_perm:[1,0,3,2] row_mask:0xf bank_mask:0xf
	v_mov_b32_dpp v96, v94 quad_perm:[1,0,3,2] row_mask:0xf bank_mask:0xf
	v_mov_b32_dpp v97, v95 quad_perm:[1,0,3,2] row_mask:0xf bank_mask:0xf
	v_mov_b32_dpp v88, v86 quad_perm:[1,0,3,2] row_mask:0xf bank_mask:0xf
	v_mov_b32_dpp v89, v87 quad_perm:[1,0,3,2] row_mask:0xf bank_mask:0xf
	v_perm_b32 v90, v92, v90, v230
	v_perm_b32 v91, v93, v91, v230
	v_perm_b32 v82, v84, v82, v230
	v_perm_b32 v83, v85, v83, v230
	v_perm_b32 v94, v96, v94, v230
	v_perm_b32 v95, v97, v95, v230
	v_perm_b32 v86, v88, v86, v230
	v_perm_b32 v87, v89, v87, v230
	global_store_dword v242, v90, s[0:1] offset:64
	global_store_dword v246, v91, s[0:1] offset:64
	global_store_dword v243, v82, s[0:1] offset:64
	global_store_dword v247, v83, s[0:1] offset:64
	global_store_dword v244, v94, s[0:1] offset:64
	global_store_dword v248, v95, s[0:1] offset:64
	global_store_dword v245, v86, s[0:1] offset:64
	global_store_dword v249, v87, s[0:1] offset:64
	v_mul_f32_e32 v74, v146, v74
	v_mul_f32_e32 v75, v146, v75
	v_mul_f32_e32 v76, v146, v76
	v_mul_f32_e32 v77, v146, v77
	v_mul_f32_e32 v66, v146, v66
	v_mul_f32_e32 v67, v146, v67
	v_mul_f32_e32 v68, v146, v68
	v_mul_f32_e32 v69, v146, v69
	v_mul_f32_e32 v78, v146, v78
	v_mul_f32_e32 v79, v146, v79
	v_mul_f32_e32 v80, v146, v80
	v_mul_f32_e32 v81, v146, v81
	v_mul_f32_e32 v70, v146, v70
	v_mul_f32_e32 v71, v146, v71
	v_mul_f32_e32 v72, v146, v72
	v_mul_f32_e32 v73, v146, v73
	v_cvt_pk_bf16_f32 v74, v74, v75
	v_cvt_pk_bf16_f32 v75, v76, v77
	v_cvt_pk_bf16_f32 v66, v66, v67
	v_cvt_pk_bf16_f32 v67, v68, v69
	v_cvt_pk_bf16_f32 v78, v78, v79
	v_cvt_pk_bf16_f32 v79, v80, v81
	v_cvt_pk_bf16_f32 v70, v70, v71
	v_cvt_pk_bf16_f32 v71, v72, v73
	v_mov_b32_dpp v76, v74 quad_perm:[1,0,3,2] row_mask:0xf bank_mask:0xf
	v_mov_b32_dpp v77, v75 quad_perm:[1,0,3,2] row_mask:0xf bank_mask:0xf
	v_mov_b32_dpp v68, v66 quad_perm:[1,0,3,2] row_mask:0xf bank_mask:0xf
	v_mov_b32_dpp v69, v67 quad_perm:[1,0,3,2] row_mask:0xf bank_mask:0xf
	v_mov_b32_dpp v80, v78 quad_perm:[1,0,3,2] row_mask:0xf bank_mask:0xf
	v_mov_b32_dpp v81, v79 quad_perm:[1,0,3,2] row_mask:0xf bank_mask:0xf
	v_mov_b32_dpp v72, v70 quad_perm:[1,0,3,2] row_mask:0xf bank_mask:0xf
	v_mov_b32_dpp v73, v71 quad_perm:[1,0,3,2] row_mask:0xf bank_mask:0xf
	v_perm_b32 v74, v76, v74, v230
	v_perm_b32 v75, v77, v75, v230
	v_perm_b32 v66, v68, v66, v230
	v_perm_b32 v67, v69, v67, v230
	v_perm_b32 v78, v80, v78, v230
	v_perm_b32 v79, v81, v79, v230
	v_perm_b32 v70, v72, v70, v230
	v_perm_b32 v71, v73, v71, v230
	global_store_dword v242, v74, s[0:1] offset:96
	global_store_dword v246, v75, s[0:1] offset:96
	global_store_dword v243, v66, s[0:1] offset:96
	global_store_dword v247, v67, s[0:1] offset:96
	global_store_dword v244, v78, s[0:1] offset:96
	global_store_dword v248, v79, s[0:1] offset:96
	global_store_dword v245, v70, s[0:1] offset:96
	global_store_dword v249, v71, s[0:1] offset:96
	v_mul_f32_e32 v58, v142, v58
	v_mul_f32_e32 v59, v142, v59
	v_mul_f32_e32 v60, v142, v60
	v_mul_f32_e32 v61, v142, v61
	v_mul_f32_e32 v50, v142, v50
	v_mul_f32_e32 v51, v142, v51
	v_mul_f32_e32 v52, v142, v52
	v_mul_f32_e32 v53, v142, v53
	v_mul_f32_e32 v62, v142, v62
	v_mul_f32_e32 v63, v142, v63
	v_mul_f32_e32 v64, v142, v64
	v_mul_f32_e32 v65, v142, v65
	v_mul_f32_e32 v54, v142, v54
	v_mul_f32_e32 v55, v142, v55
	v_mul_f32_e32 v56, v142, v56
	v_mul_f32_e32 v57, v142, v57
	v_cvt_pk_bf16_f32 v58, v58, v59
	v_cvt_pk_bf16_f32 v59, v60, v61
	v_cvt_pk_bf16_f32 v50, v50, v51
	v_cvt_pk_bf16_f32 v51, v52, v53
	v_cvt_pk_bf16_f32 v62, v62, v63
	v_cvt_pk_bf16_f32 v63, v64, v65
	v_cvt_pk_bf16_f32 v54, v54, v55
	v_cvt_pk_bf16_f32 v55, v56, v57
	v_mov_b32_dpp v60, v58 quad_perm:[1,0,3,2] row_mask:0xf bank_mask:0xf
	v_mov_b32_dpp v61, v59 quad_perm:[1,0,3,2] row_mask:0xf bank_mask:0xf
	v_mov_b32_dpp v52, v50 quad_perm:[1,0,3,2] row_mask:0xf bank_mask:0xf
	v_mov_b32_dpp v53, v51 quad_perm:[1,0,3,2] row_mask:0xf bank_mask:0xf
	v_mov_b32_dpp v64, v62 quad_perm:[1,0,3,2] row_mask:0xf bank_mask:0xf
	v_mov_b32_dpp v65, v63 quad_perm:[1,0,3,2] row_mask:0xf bank_mask:0xf
	v_mov_b32_dpp v56, v54 quad_perm:[1,0,3,2] row_mask:0xf bank_mask:0xf
	v_mov_b32_dpp v57, v55 quad_perm:[1,0,3,2] row_mask:0xf bank_mask:0xf
	v_perm_b32 v58, v60, v58, v230
	v_perm_b32 v59, v61, v59, v230
	v_perm_b32 v50, v52, v50, v230
	v_perm_b32 v51, v53, v51, v230
	v_perm_b32 v62, v64, v62, v230
	v_perm_b32 v63, v65, v63, v230
	v_perm_b32 v54, v56, v54, v230
	v_perm_b32 v55, v57, v55, v230
	global_store_dword v242, v58, s[0:1] offset:256
	global_store_dword v246, v59, s[0:1] offset:256
	global_store_dword v243, v50, s[0:1] offset:256
	global_store_dword v247, v51, s[0:1] offset:256
	global_store_dword v244, v62, s[0:1] offset:256
	global_store_dword v248, v63, s[0:1] offset:256
	global_store_dword v245, v54, s[0:1] offset:256
	global_store_dword v249, v55, s[0:1] offset:256
	v_mul_f32_e32 v42, v138, v42
	v_mul_f32_e32 v43, v138, v43
	v_mul_f32_e32 v44, v138, v44
	v_mul_f32_e32 v45, v138, v45
	v_mul_f32_e32 v34, v138, v34
	v_mul_f32_e32 v35, v138, v35
	v_mul_f32_e32 v36, v138, v36
	v_mul_f32_e32 v37, v138, v37
	v_mul_f32_e32 v46, v138, v46
	v_mul_f32_e32 v47, v138, v47
	v_mul_f32_e32 v48, v138, v48
; __device__ __forceinline__ unsigned cvt_pk_bf16(float lo, float hi) { unsigned r; asm volatile("v_cvt_pk_bf16_f32 %0, %1, %2" : "=v"(r) : "v"(lo), "v"(hi)); return r; }
;     __device__ __forceinline__ void operator()(const f32x4 (&acc)[2][2][4][2], const Unit& u, int wr, int wc, int fr_, int fq_) const {
;     ...
;         } else if (pn == 7 || pn == 8) {
; #pragma unroll
;             for (int ai = 0; ai < 2; ++ai)
; #pragma unroll
;                 for (int m = 0; m < 4; ++m) {
;                     const int row = u.pm * 256 + ai * 128 + wr * 64 + m * 16 + fr;
;                     const float rs = rs8[ai][m];
;                     bf16_t* dst = VB + (size_t)(256 * (pn - 7) + 64 * wc + 16 * fq) * Mg + row;
; #pragma unroll
;                     for (int bj = 0; bj < 2; ++bj)
; #pragma unroll
;                         for (int n = 0; n < 2; ++n) { const f32x4 a = acc[ai][bj][m][n] * rs; const unsigned w0 = cvt_pk_bf16(a[0], a[1]), w1 = cvt_pk_bf16(a[2], a[3]);
;                             bf16_t* d = dst + (size_t)(8 * bj + 4 * n) * Mg;
;                             d[0] = (bf16_t)w0; d[(size_t)Mg] = (bf16_t)(w0 >> 16); d[2 * (size_t)Mg] = (bf16_t)w1; d[3 * (size_t)Mg] = (bf16_t)(w1 >> 16); }
;                 }
	v_mul_f32_e32 v49, v138, v49
	v_mul_f32_e32 v38, v138, v38
	v_mul_f32_e32 v39, v138, v39
	v_mul_f32_e32 v40, v138, v40
	v_mul_f32_e32 v41, v138, v41
	v_cvt_pk_bf16_f32 v42, v42, v43
	v_cvt_pk_bf16_f32 v43, v44, v45
	v_cvt_pk_bf16_f32 v34, v34, v35
	v_cvt_pk_bf16_f32 v35, v36, v37
	v_cvt_pk_bf16_f32 v46, v46, v47
	v_cvt_pk_bf16_f32 v47, v48, v49
	v_cvt_pk_bf16_f32 v38, v38, v39
	v_cvt_pk_bf16_f32 v39, v40, v41
	v_mov_b32_dpp v44, v42 quad_perm:[1,0,3,2] row_mask:0xf bank_mask:0xf
	v_mov_b32_dpp v45, v43 quad_perm:[1,0,3,2] row_mask:0xf bank_mask:0xf
	v_mov_b32_dpp v36, v34 quad_perm:[1,0,3,2] row_mask:0xf bank_mask:0xf
	v_mov_b32_dpp v37, v35 quad_perm:[1,0,3,2] row_mask:0xf bank_mask:0xf
	v_mov_b32_dpp v48, v46 quad_perm:[1,0,3,2] row_mask:0xf bank_mask:0xf
	v_mov_b32_dpp v49, v47 quad_perm:[1,0,3,2] row_mask:0xf bank_mask:0xf
	v_mov_b32_dpp v40, v38 quad_perm:[1,0,3,2] row_mask:0xf bank_mask:0xf
	v_mov_b32_dpp v41, v39 quad_perm:[1,0,3,2] row_mask:0xf bank_mask:0xf
	v_perm_b32 v42, v44, v42, v230
	v_perm_b32 v43, v45, v43, v230
	v_perm_b32 v34, v36, v34, v230
	v_perm_b32 v35, v37, v35, v230
	v_perm_b32 v46, v48, v46, v230
	v_perm_b32 v47, v49, v47, v230
	v_perm_b32 v38, v40, v38, v230
	v_perm_b32 v39, v41, v39, v230
	global_store_dword v242, v42, s[0:1] offset:288
	global_store_dword v246, v43, s[0:1] offset:288
	global_store_dword v243, v34, s[0:1] offset:288
	global_store_dword v247, v35, s[0:1] offset:288
	global_store_dword v244, v46, s[0:1] offset:288
	global_store_dword v248, v47, s[0:1] offset:288
	global_store_dword v245, v38, s[0:1] offset:288
	global_store_dword v249, v39, s[0:1] offset:288
	v_mul_f32_e32 v26, v132, v26
	v_mul_f32_e32 v27, v132, v27
	v_mul_f32_e32 v28, v132, v28
	v_mul_f32_e32 v29, v132, v29
	v_mul_f32_e32 v18, v132, v18
	v_mul_f32_e32 v19, v132, v19
	v_mul_f32_e32 v20, v132, v20
	v_mul_f32_e32 v21, v132, v21
	v_mul_f32_e32 v30, v132, v30
	v_mul_f32_e32 v31, v132, v31
	v_mul_f32_e32 v32, v132, v32
	v_mul_f32_e32 v33, v132, v33
	v_mul_f32_e32 v22, v132, v22
	v_mul_f32_e32 v23, v132, v23
	v_mul_f32_e32 v24, v132, v24
	v_mul_f32_e32 v25, v132, v25
	v_cvt_pk_bf16_f32 v26, v26, v27
	v_cvt_pk_bf16_f32 v27, v28, v29
	v_cvt_pk_bf16_f32 v18, v18, v19
	v_cvt_pk_bf16_f32 v19, v20, v21
	v_cvt_pk_bf16_f32 v30, v30, v31
	v_cvt_pk_bf16_f32 v31, v32, v33
	v_cvt_pk_bf16_f32 v22, v22, v23
	v_cvt_pk_bf16_f32 v23, v24, v25
	v_mov_b32_dpp v28, v26 quad_perm:[1,0,3,2] row_mask:0xf bank_mask:0xf
	v_mov_b32_dpp v29, v27 quad_perm:[1,0,3,2] row_mask:0xf bank_mask:0xf
	v_mov_b32_dpp v20, v18 quad_perm:[1,0,3,2] row_mask:0xf bank_mask:0xf
	v_mov_b32_dpp v21, v19 quad_perm:[1,0,3,2] row_mask:0xf bank_mask:0xf
	v_mov_b32_dpp v32, v30 quad_perm:[1,0,3,2] row_mask:0xf bank_mask:0xf
	v_mov_b32_dpp v33, v31 quad_perm:[1,0,3,2] row_mask:0xf bank_mask:0xf
	v_mov_b32_dpp v24, v22 quad_perm:[1,0,3,2] row_mask:0xf bank_mask:0xf
	v_mov_b32_dpp v25, v23 quad_perm:[1,0,3,2] row_mask:0xf bank_mask:0xf
	v_perm_b32 v26, v28, v26, v230
	v_perm_b32 v27, v29, v27, v230
	v_perm_b32 v18, v20, v18, v230
	v_perm_b32 v19, v21, v19, v230
	v_perm_b32 v30, v32, v30, v230
	v_perm_b32 v31, v33, v31, v230
	v_perm_b32 v22, v24, v22, v230
	v_perm_b32 v23, v25, v23, v230
	global_store_dword v242, v26, s[0:1] offset:320
	global_store_dword v246, v27, s[0:1] offset:320
	global_store_dword v243, v18, s[0:1] offset:320
	global_store_dword v247, v19, s[0:1] offset:320
	global_store_dword v244, v30, s[0:1] offset:320
	global_store_dword v248, v31, s[0:1] offset:320
	global_store_dword v245, v22, s[0:1] offset:320
	global_store_dword v249, v23, s[0:1] offset:320
	v_mul_f32_e32 v10, v130, v10
	v_mul_f32_e32 v11, v130, v11
	v_mul_f32_e32 v12, v130, v12
	v_mul_f32_e32 v13, v130, v13
	v_mul_f32_e32 v2, v130, v2
	v_mul_f32_e32 v3, v130, v3
	v_mul_f32_e32 v4, v130, v4
	v_mul_f32_e32 v5, v130, v5
	v_mul_f32_e32 v14, v130, v14
	v_mul_f32_e32 v15, v130, v15
	v_mul_f32_e32 v16, v130, v16
	v_mul_f32_e32 v17, v130, v17
	v_mul_f32_e32 v6, v130, v6
	v_mul_f32_e32 v7, v130, v7
	v_mul_f32_e32 v8, v130, v8
	v_mul_f32_e32 v9, v130, v9
	v_cvt_pk_bf16_f32 v10, v10, v11
	v_cvt_pk_bf16_f32 v11, v12, v13
	v_cvt_pk_bf16_f32 v2, v2, v3
	v_cvt_pk_bf16_f32 v3, v4, v5
	v_cvt_pk_bf16_f32 v14, v14, v15
	v_cvt_pk_bf16_f32 v15, v16, v17
	v_cvt_pk_bf16_f32 v6, v6, v7
	v_cvt_pk_bf16_f32 v7, v8, v9
	v_mov_b32_dpp v12, v10 quad_perm:[1,0,3,2] row_mask:0xf bank_mask:0xf
	v_mov_b32_dpp v13, v11 quad_perm:[1,0,3,2] row_mask:0xf bank_mask:0xf
	v_mov_b32_dpp v4, v2 quad_perm:[1,0,3,2] row_mask:0xf bank_mask:0xf
	v_mov_b32_dpp v5, v3 quad_perm:[1,0,3,2] row_mask:0xf bank_mask:0xf
	v_mov_b32_dpp v16, v14 quad_perm:[1,0,3,2] row_mask:0xf bank_mask:0xf
	v_mov_b32_dpp v17, v15 quad_perm:[1,0,3,2] row_mask:0xf bank_mask:0xf
	v_mov_b32_dpp v8, v6 quad_perm:[1,0,3,2] row_mask:0xf bank_mask:0xf
	v_mov_b32_dpp v9, v7 quad_perm:[1,0,3,2] row_mask:0xf bank_mask:0xf
	v_perm_b32 v10, v12, v10, v230
	v_perm_b32 v11, v13, v11, v230
	v_perm_b32 v2, v4, v2, v230
	v_perm_b32 v3, v5, v3, v230
	v_perm_b32 v14, v16, v14, v230
	v_perm_b32 v15, v17, v15, v230
	v_perm_b32 v6, v8, v6, v230
	v_perm_b32 v7, v9, v7, v230
	global_store_dword v242, v10, s[0:1] offset:352
	global_store_dword v246, v11, s[0:1] offset:352
	global_store_dword v243, v2, s[0:1] offset:352
	global_store_dword v247, v3, s[0:1] offset:352
	global_store_dword v244, v14, s[0:1] offset:352
	global_store_dword v248, v15, s[0:1] offset:352
	global_store_dword v245, v6, s[0:1] offset:352
	global_store_dword v249, v7, s[0:1] offset:352
